# PEER fp8 table build moved from the ffn_norm phase into the idle tail of the merge-GEMM phase (table relocated to the dead sample-V^T region)
# speedup vs baseline: 1.0072x; 1.0023x over previous
; __device__ void phase_ffn_norm(const Params& p) {
;     ...
;   unsigned char* q8 = (unsigned char*)(ws + W_F); float* qs = (float*)(ws + W_F + 33554432);
;   for (int r = gw; r < 2 * 16384; r += nw) {
;     const float* src = (r < 16384) ? p.in[22] + (size_t)r * DM : p.in[23] + (size_t)(r - 16384) * DM;
;     f32x4 v[4]; float am = 0.f;
; #pragma unroll
;     for (int i = 0; i < 4; ++i) { v[i] = *(const f32x4*)(src + lane * 16 + i * 4); am = fmaxf(am, fmaxf(fmaxf(fabsf(v[i][0]), fabsf(v[i][1])), fmaxf(fabsf(v[i][2]), fabsf(v[i][3])))); }
.LBB0_830:
	v_writelane_b32 v244, s10, 0
	v_writelane_b32 v244, s11, 1
	v_writelane_b32 v244, s12, 2
	v_writelane_b32 v244, s13, 3
	v_writelane_b32 v244, s40, 4
	v_writelane_b32 v244, s41, 5
	v_writelane_b32 v244, s42, 6
	v_writelane_b32 v244, s43, 7
	v_writelane_b32 v244, s44, 8
	v_writelane_b32 v244, s45, 9
	v_writelane_b32 v244, s46, 10
	v_writelane_b32 v244, s47, 11
	v_writelane_b32 v244, s48, 12
	v_writelane_b32 v244, s49, 13
	v_writelane_b32 v244, s50, 14
	v_writelane_b32 v244, s51, 15
	v_writelane_b32 v244, s58, 16
	v_writelane_b32 v244, s59, 17
	v_writelane_b32 v244, s60, 18
	v_writelane_b32 v244, s61, 19
	v_writelane_b32 v244, s62, 20
	v_writelane_b32 v244, s63, 21
	v_writelane_b32 v244, s64, 22
	v_writelane_b32 v244, s65, 23
	v_writelane_b32 v244, s66, 24
	v_writelane_b32 v244, s67, 25
	v_writelane_b32 v244, s68, 26
	v_writelane_b32 v244, s70, 27
	v_writelane_b32 v244, s71, 28
	v_writelane_b32 v244, vcc_lo, 29
	v_writelane_b32 v244, vcc_hi, 30
	s_mov_b64 s[66:67], exec
	s_mov_b64 exec, -1
	s_waitcnt lgkmcnt(0)
	s_barrier
	v_lshlrev_b32_e32 v245, 2, v181
	ds_write_b32 v245, v0 offset:0
	ds_write_b32 v245, v1 offset:1024
	ds_write_b32 v245, v2 offset:2048
	ds_write_b32 v245, v3 offset:3072
	ds_write_b32 v245, v4 offset:4096
	ds_write_b32 v245, v5 offset:5120
	ds_write_b32 v245, v6 offset:6144
	ds_write_b32 v245, v7 offset:7168
	ds_write_b32 v245, v8 offset:8192
	ds_write_b32 v245, v9 offset:9216
	ds_write_b32 v245, v10 offset:10240
	ds_write_b32 v245, v11 offset:11264
	ds_write_b32 v245, v12 offset:12288
	ds_write_b32 v245, v13 offset:13312
	ds_write_b32 v245, v14 offset:14336
	ds_write_b32 v245, v15 offset:15360
	ds_write_b32 v245, v16 offset:16384
	ds_write_b32 v245, v17 offset:17408
	ds_write_b32 v245, v18 offset:18432
	ds_write_b32 v245, v19 offset:19456
	ds_write_b32 v245, v20 offset:20480
	ds_write_b32 v245, v21 offset:21504
	ds_write_b32 v245, v22 offset:22528
	ds_write_b32 v245, v23 offset:23552
	ds_write_b32 v245, v24 offset:24576
	ds_write_b32 v245, v25 offset:25600
	ds_write_b32 v245, v26 offset:26624
	ds_write_b32 v245, v27 offset:27648
	ds_write_b32 v245, v28 offset:28672
	ds_write_b32 v245, v29 offset:29696
	ds_write_b32 v245, v30 offset:30720
	ds_write_b32 v245, v31 offset:31744
	ds_write_b32 v245, v32 offset:32768
	ds_write_b32 v245, v33 offset:33792
	ds_write_b32 v245, v34 offset:34816
	ds_write_b32 v245, v35 offset:35840
	ds_write_b32 v245, v36 offset:36864
	ds_write_b32 v245, v37 offset:37888
	ds_write_b32 v245, v38 offset:38912
	ds_write_b32 v245, v39 offset:39936
	ds_write_b32 v245, v40 offset:40960
	ds_write_b32 v245, v41 offset:41984
	ds_write_b32 v245, v42 offset:43008
	ds_write_b32 v245, v43 offset:44032
	ds_write_b32 v245, v44 offset:45056
	ds_write_b32 v245, v45 offset:46080
	ds_write_b32 v245, v46 offset:47104
	ds_write_b32 v245, v47 offset:48128
	ds_write_b32 v245, v48 offset:49152
	ds_write_b32 v245, v49 offset:50176
	ds_write_b32 v245, v50 offset:51200
	ds_write_b32 v245, v51 offset:52224
	s_waitcnt lgkmcnt(0)
	v_readlane_b32 s40, v248, 33
	v_readfirstlane_b32 s41, v181
	s_nop 1
	s_lshr_b32 s41, s41, 6
	s_cmp_lt_u32 s40, 64
	s_cbranch_scc0 .Lcv_hi
	s_bitcmp1_b32 s40, 0
	s_cbranch_scc1 .Lcv_done
	s_lshr_b32 s40, s40, 1
	s_branch .Lcv_rank
.Lcv_hi:
	s_sub_i32 s40, s40, 32
.Lcv_rank:
	s_lshl_b32 s40, s40, 2
	s_add_i32 s40, s40, s41
	v_readlane_b32 s10, v248, 23
	v_readlane_b32 s11, v248, 24
	v_readlane_b32 s12, v248, 25
	v_readlane_b32 s13, v248, 26
	s_add_u32 s58, s96, 0x1489e000
	s_addc_u32 s59, s97, 0
	v_lshlrev_b32_e32 v0, 6, v180
	v_lshlrev_b32_e32 v1, 4, v180
	v_mov_b32_e32 v9, 0
	v_mov_b32_e32 v8, 0x43600000
	v_xor_b32_e32 v2, 32, v180
	v_lshlrev_b32_e32 v2, 2, v2
	v_xor_b32_e32 v3, 16, v180
	v_lshlrev_b32_e32 v3, 2, v3
	v_xor_b32_e32 v4, 8, v180
	v_lshlrev_b32_e32 v4, 2, v4
	v_xor_b32_e32 v5, 4, v180
	v_lshlrev_b32_e32 v5, 2, v5
	v_xor_b32_e32 v6, 2, v180
	v_lshlrev_b32_e32 v6, 2, v6
	v_xor_b32_e32 v7, 1, v180
	v_lshlrev_b32_e32 v7, 2, v7
.Lcv_loop:
	s_and_b32 s41, s40, 0x3fff
	s_cmp_lt_u32 s40, 0x4000
	s_cselect_b32 s42, s10, s12
	s_cselect_b32 s43, s11, s13
	s_cselect_b32 s45, 0, 0x400
	s_lshl_b32 s44, s41, 12
	s_add_u32 s42, s42, s44
	s_addc_u32 s43, s43, 0
	s_lshl_b32 s44, s41, 11
	s_add_i32 s44, s44, s45
	s_add_u32 s46, s58, s44
	s_addc_u32 s47, s59, 0
	s_lshl_b32 s44, s40, 2
	s_add_u32 s48, s58, s44
	s_addc_u32 s49, s59, 0
	s_add_u32 s48, s48, 0x2000000
	s_addc_u32 s49, s49, 0
	global_load_dwordx4 v[16:19], v0, s[42:43]
	global_load_dwordx4 v[20:23], v0, s[42:43] offset:16
	global_load_dwordx4 v[24:27], v0, s[42:43] offset:32
	global_load_dwordx4 v[28:31], v0, s[42:43] offset:48
	s_add_i32 s68, s40, 0x780
	s_cmp_lt_u32 s68, 0x8000
	s_cbranch_scc0 .Lcv_single
; __device__ void phase_ffn_norm(const Params& p) {
;     ...
;   for (int r = gw; r < 2 * 16384; r += nw) {
;     const float* src = (r < 16384) ? p.in[22] + (size_t)r * DM : p.in[23] + (size_t)(r - 16384) * DM;
;     f32x4 v[4]; float am = 0.f;
; #pragma unroll
;     for (int i = 0; i < 4; ++i) { v[i] = *(const f32x4*)(src + lane * 16 + i * 4); am = fmaxf(am, fmaxf(fmaxf(fabsf(v[i][0]), fabsf(v[i][1])), fmaxf(fabsf(v[i][2]), fabsf(v[i][3])))); }
; #pragma unroll
;     for (int o = 32; o >= 1; o >>= 1) am = fmaxf(am, __shfl_xor(am, o));
;     const float sc = am > 0.f ? 224.f / am : 1.f;
;     u32x4 w;
; #pragma unroll
;     for (int i = 0; i < 4; ++i) {
;       int d = 0;
;       d = __builtin_amdgcn_cvt_pk_fp8_f32(v[i][0] * sc, v[i][1] * sc, d, false);
;       d = __builtin_amdgcn_cvt_pk_fp8_f32(v[i][2] * sc, v[i][3] * sc, d, true);
;       w[i] = (unsigned)d;
;     }
;     *(u32x4*)(q8 + (r < 16384 ? (size_t)r * 2048 : (size_t)(r - 16384) * 2048 + 1024) + lane * 16) = w;
;     if (lane == 0) qs[r] = am > 0.f ? am / 224.f : 1.f;
;   }
	s_and_b32 s41, s68, 0x3fff
	s_cmp_lt_u32 s68, 0x4000
	s_cselect_b32 s60, s10, s12
	s_cselect_b32 s61, s11, s13
	s_cselect_b32 s45, 0, 0x400
	s_lshl_b32 s44, s41, 12
	s_add_u32 s60, s60, s44
	s_addc_u32 s61, s61, 0
	s_lshl_b32 s44, s41, 11
	s_add_i32 s44, s44, s45
	s_add_u32 s62, s58, s44
	s_addc_u32 s63, s59, 0
	s_lshl_b32 s44, s68, 2
	s_add_u32 s64, s58, s44
	s_addc_u32 s65, s59, 0
	s_add_u32 s64, s64, 0x2000000
	s_addc_u32 s65, s65, 0
	global_load_dwordx4 v[32:35], v0, s[60:61]
	global_load_dwordx4 v[36:39], v0, s[60:61] offset:16
	global_load_dwordx4 v[40:43], v0, s[60:61] offset:32
	global_load_dwordx4 v[44:47], v0, s[60:61] offset:48
	s_waitcnt vmcnt(4)
	v_mov_b32_e32 v10, 0
	v_max3_f32 v10, |v16|, |v17|, v10
	v_max3_f32 v10, |v18|, |v19|, v10
	v_max3_f32 v10, |v20|, |v21|, v10
	v_max3_f32 v10, |v22|, |v23|, v10
	v_max3_f32 v10, |v24|, |v25|, v10
	v_max3_f32 v10, |v26|, |v27|, v10
	v_max3_f32 v10, |v28|, |v29|, v10
	v_max3_f32 v10, |v30|, |v31|, v10
	ds_bpermute_b32 v11, v2, v10
	s_waitcnt lgkmcnt(0)
	v_max_f32_e32 v10, v10, v11
	ds_bpermute_b32 v11, v3, v10
	s_waitcnt lgkmcnt(0)
	v_max_f32_e32 v10, v10, v11
	ds_bpermute_b32 v11, v4, v10
	s_waitcnt lgkmcnt(0)
	v_max_f32_e32 v10, v10, v11
	ds_bpermute_b32 v11, v5, v10
	s_waitcnt lgkmcnt(0)
	v_max_f32_e32 v10, v10, v11
	ds_bpermute_b32 v11, v6, v10
	s_waitcnt lgkmcnt(0)
	v_max_f32_e32 v10, v10, v11
	ds_bpermute_b32 v11, v7, v10
	s_waitcnt lgkmcnt(0)
	v_max_f32_e32 v10, v10, v11
	v_div_scale_f32 v11, s[50:51], v10, v10, v8
	v_rcp_f32_e32 v12, v11
	v_div_scale_f32 v13, vcc, v8, v10, v8
	v_cmp_lt_f32_e64 s[70:71], 0, v10
	v_fma_f32 v14, -v11, v12, 1.0
	v_fmac_f32_e32 v12, v14, v12
	v_mul_f32_e32 v14, v13, v12
	v_fma_f32 v15, -v11, v14, v13
	v_fmac_f32_e32 v14, v15, v12
	v_fma_f32 v13, -v11, v14, v13
	v_div_fmas_f32 v13, v13, v12, v14
	v_div_fixup_f32 v13, v13, v10, v8
	v_cndmask_b32_e64 v13, 1.0, v13, s[70:71]
	v_mul_f32_e32 v16, v16, v13
	v_mul_f32_e32 v17, v17, v13
	v_mul_f32_e32 v18, v18, v13
	v_mul_f32_e32 v19, v19, v13
	v_mul_f32_e32 v20, v20, v13
	v_mul_f32_e32 v21, v21, v13
	v_mul_f32_e32 v22, v22, v13
	v_mul_f32_e32 v23, v23, v13
	v_mul_f32_e32 v24, v24, v13
	v_mul_f32_e32 v25, v25, v13
	v_mul_f32_e32 v26, v26, v13
	v_mul_f32_e32 v27, v27, v13
	v_mul_f32_e32 v28, v28, v13
	v_mul_f32_e32 v29, v29, v13
	v_mul_f32_e32 v30, v30, v13
	v_mul_f32_e32 v31, v31, v13
	v_mov_b32_e32 v48, 0
	v_mov_b32_e32 v49, 0
	v_mov_b32_e32 v50, 0
	v_mov_b32_e32 v51, 0
	v_cvt_pk_fp8_f32 v48, v16, v17
	v_cvt_pk_fp8_f32 v49, v20, v21
	v_cvt_pk_fp8_f32 v50, v24, v25
	v_cvt_pk_fp8_f32 v51, v28, v29
	v_cvt_pk_fp8_f32 v48, v18, v19 op_sel:[0,0,1]
	v_cvt_pk_fp8_f32 v49, v22, v23 op_sel:[0,0,1]
	v_cvt_pk_fp8_f32 v50, v26, v27 op_sel:[0,0,1]
	v_cvt_pk_fp8_f32 v51, v30, v31 op_sel:[0,0,1]
	v_div_scale_f32 v11, s[50:51], v8, v8, v10
	v_rcp_f32_e32 v12, v11
	v_div_scale_f32 v13, vcc, v10, v8, v10
	v_fma_f32 v14, -v11, v12, 1.0
	v_fmac_f32_e32 v12, v14, v12
	v_mul_f32_e32 v14, v13, v12
	v_fma_f32 v15, -v11, v14, v13
	v_fmac_f32_e32 v14, v15, v12
	v_fma_f32 v11, -v11, v14, v13
	v_div_fmas_f32 v11, v11, v12, v14
	v_div_fixup_f32 v11, v11, v8, v10
	v_cndmask_b32_e64 v11, 1.0, v11, s[70:71]
	global_store_dwordx4 v1, v[48:51], s[46:47]
	s_mov_b64 exec, 1
	global_store_dword v9, v11, s[48:49]
	s_mov_b64 exec, -1
	s_waitcnt vmcnt(2)
	v_mov_b32_e32 v10, 0
	v_max3_f32 v10, |v32|, |v33|, v10
	v_max3_f32 v10, |v34|, |v35|, v10
	v_max3_f32 v10, |v36|, |v37|, v10
	v_max3_f32 v10, |v38|, |v39|, v10
	v_max3_f32 v10, |v40|, |v41|, v10
	v_max3_f32 v10, |v42|, |v43|, v10
	v_max3_f32 v10, |v44|, |v45|, v10
	v_max3_f32 v10, |v46|, |v47|, v10
	ds_bpermute_b32 v11, v2, v10
	s_waitcnt lgkmcnt(0)
	v_max_f32_e32 v10, v10, v11
	ds_bpermute_b32 v11, v3, v10
	s_waitcnt lgkmcnt(0)
	v_max_f32_e32 v10, v10, v11
	ds_bpermute_b32 v11, v4, v10
	s_waitcnt lgkmcnt(0)
	v_max_f32_e32 v10, v10, v11
	ds_bpermute_b32 v11, v5, v10
	s_waitcnt lgkmcnt(0)
	v_max_f32_e32 v10, v10, v11
	ds_bpermute_b32 v11, v6, v10
	s_waitcnt lgkmcnt(0)
	v_max_f32_e32 v10, v10, v11
	ds_bpermute_b32 v11, v7, v10
	s_waitcnt lgkmcnt(0)
	v_max_f32_e32 v10, v10, v11
	v_div_scale_f32 v11, s[50:51], v10, v10, v8
	v_rcp_f32_e32 v12, v11
	v_div_scale_f32 v13, vcc, v8, v10, v8
	v_cmp_lt_f32_e64 s[70:71], 0, v10
	v_fma_f32 v14, -v11, v12, 1.0
	v_fmac_f32_e32 v12, v14, v12
	v_mul_f32_e32 v14, v13, v12
	v_fma_f32 v15, -v11, v14, v13
	v_fmac_f32_e32 v14, v15, v12
	v_fma_f32 v13, -v11, v14, v13
	v_div_fmas_f32 v13, v13, v12, v14
	v_div_fixup_f32 v13, v13, v10, v8
	v_cndmask_b32_e64 v13, 1.0, v13, s[70:71]
	v_mul_f32_e32 v32, v32, v13
	v_mul_f32_e32 v33, v33, v13
	v_mul_f32_e32 v34, v34, v13
	v_mul_f32_e32 v35, v35, v13
	v_mul_f32_e32 v36, v36, v13
	v_mul_f32_e32 v37, v37, v13
	v_mul_f32_e32 v38, v38, v13
	v_mul_f32_e32 v39, v39, v13
	v_mul_f32_e32 v40, v40, v13
	v_mul_f32_e32 v41, v41, v13
	v_mul_f32_e32 v42, v42, v13
	v_mul_f32_e32 v43, v43, v13
	v_mul_f32_e32 v44, v44, v13
	v_mul_f32_e32 v45, v45, v13
	v_mul_f32_e32 v46, v46, v13
	v_mul_f32_e32 v47, v47, v13
	v_mov_b32_e32 v48, 0
	v_mov_b32_e32 v49, 0
	v_mov_b32_e32 v50, 0
	v_mov_b32_e32 v51, 0
	v_cvt_pk_fp8_f32 v48, v32, v33
	v_cvt_pk_fp8_f32 v49, v36, v37
	v_cvt_pk_fp8_f32 v50, v40, v41
	v_cvt_pk_fp8_f32 v51, v44, v45
	v_cvt_pk_fp8_f32 v48, v34, v35 op_sel:[0,0,1]
	v_cvt_pk_fp8_f32 v49, v38, v39 op_sel:[0,0,1]
	v_cvt_pk_fp8_f32 v50, v42, v43 op_sel:[0,0,1]
	v_cvt_pk_fp8_f32 v51, v46, v47 op_sel:[0,0,1]
	v_div_scale_f32 v11, s[50:51], v8, v8, v10
	v_rcp_f32_e32 v12, v11
	v_div_scale_f32 v13, vcc, v10, v8, v10
	v_fma_f32 v14, -v11, v12, 1.0
	v_fmac_f32_e32 v12, v14, v12
	v_mul_f32_e32 v14, v13, v12
	v_fma_f32 v15, -v11, v14, v13
	v_fmac_f32_e32 v14, v15, v12
	v_fma_f32 v11, -v11, v14, v13
	v_div_fmas_f32 v11, v11, v12, v14
	v_div_fixup_f32 v11, v11, v8, v10
	v_cndmask_b32_e64 v11, 1.0, v11, s[70:71]
	global_store_dwordx4 v1, v[48:51], s[62:63]
	s_mov_b64 exec, 1
	global_store_dword v9, v11, s[64:65]
	s_mov_b64 exec, -1
	s_add_i32 s40, s40, 0xf00
	s_cmp_lt_u32 s40, 0x8000
	s_cbranch_scc1 .Lcv_loop
	s_branch .Lcv_done
; __device__ void phase_ffn_norm(const Params& p) {
;     ...
;   for (int r = gw; r < 2 * 16384; r += nw) {
;     const float* src = (r < 16384) ? p.in[22] + (size_t)r * DM : p.in[23] + (size_t)(r - 16384) * DM;
;     f32x4 v[4]; float am = 0.f;
; #pragma unroll
;     for (int i = 0; i < 4; ++i) { v[i] = *(const f32x4*)(src + lane * 16 + i * 4); am = fmaxf(am, fmaxf(fmaxf(fabsf(v[i][0]), fabsf(v[i][1])), fmaxf(fabsf(v[i][2]), fabsf(v[i][3])))); }
; #pragma unroll
;     for (int o = 32; o >= 1; o >>= 1) am = fmaxf(am, __shfl_xor(am, o));
;     const float sc = am > 0.f ? 224.f / am : 1.f;
;     u32x4 w;
; #pragma unroll
;     for (int i = 0; i < 4; ++i) {
;       int d = 0;
;       d = __builtin_amdgcn_cvt_pk_fp8_f32(v[i][0] * sc, v[i][1] * sc, d, false);
;       d = __builtin_amdgcn_cvt_pk_fp8_f32(v[i][2] * sc, v[i][3] * sc, d, true);
;       w[i] = (unsigned)d;
;     }
;     *(u32x4*)(q8 + (r < 16384 ? (size_t)r * 2048 : (size_t)(r - 16384) * 2048 + 1024) + lane * 16) = w;
;     if (lane == 0) qs[r] = am > 0.f ? am / 224.f : 1.f;
;   }
.Lcv_single:
	s_waitcnt vmcnt(0)
	v_mov_b32_e32 v10, 0
	v_max3_f32 v10, |v16|, |v17|, v10
	v_max3_f32 v10, |v18|, |v19|, v10
	v_max3_f32 v10, |v20|, |v21|, v10
	v_max3_f32 v10, |v22|, |v23|, v10
	v_max3_f32 v10, |v24|, |v25|, v10
	v_max3_f32 v10, |v26|, |v27|, v10
	v_max3_f32 v10, |v28|, |v29|, v10
	v_max3_f32 v10, |v30|, |v31|, v10
	ds_bpermute_b32 v11, v2, v10
	s_waitcnt lgkmcnt(0)
	v_max_f32_e32 v10, v10, v11
	ds_bpermute_b32 v11, v3, v10
	s_waitcnt lgkmcnt(0)
	v_max_f32_e32 v10, v10, v11
	ds_bpermute_b32 v11, v4, v10
	s_waitcnt lgkmcnt(0)
	v_max_f32_e32 v10, v10, v11
	ds_bpermute_b32 v11, v5, v10
	s_waitcnt lgkmcnt(0)
	v_max_f32_e32 v10, v10, v11
	ds_bpermute_b32 v11, v6, v10
	s_waitcnt lgkmcnt(0)
	v_max_f32_e32 v10, v10, v11
	ds_bpermute_b32 v11, v7, v10
	s_waitcnt lgkmcnt(0)
	v_max_f32_e32 v10, v10, v11
	v_div_scale_f32 v11, s[50:51], v10, v10, v8
	v_rcp_f32_e32 v12, v11
	v_div_scale_f32 v13, vcc, v8, v10, v8
	v_cmp_lt_f32_e64 s[70:71], 0, v10
	v_fma_f32 v14, -v11, v12, 1.0
	v_fmac_f32_e32 v12, v14, v12
	v_mul_f32_e32 v14, v13, v12
	v_fma_f32 v15, -v11, v14, v13
	v_fmac_f32_e32 v14, v15, v12
	v_fma_f32 v13, -v11, v14, v13
	v_div_fmas_f32 v13, v13, v12, v14
	v_div_fixup_f32 v13, v13, v10, v8
	v_cndmask_b32_e64 v13, 1.0, v13, s[70:71]
	v_mul_f32_e32 v16, v16, v13
	v_mul_f32_e32 v17, v17, v13
	v_mul_f32_e32 v18, v18, v13
	v_mul_f32_e32 v19, v19, v13
	v_mul_f32_e32 v20, v20, v13
	v_mul_f32_e32 v21, v21, v13
	v_mul_f32_e32 v22, v22, v13
	v_mul_f32_e32 v23, v23, v13
	v_mul_f32_e32 v24, v24, v13
	v_mul_f32_e32 v25, v25, v13
	v_mul_f32_e32 v26, v26, v13
	v_mul_f32_e32 v27, v27, v13
	v_mul_f32_e32 v28, v28, v13
	v_mul_f32_e32 v29, v29, v13
	v_mul_f32_e32 v30, v30, v13
	v_mul_f32_e32 v31, v31, v13
	v_mov_b32_e32 v48, 0
	v_mov_b32_e32 v49, 0
	v_mov_b32_e32 v50, 0
	v_mov_b32_e32 v51, 0
	v_cvt_pk_fp8_f32 v48, v16, v17
	v_cvt_pk_fp8_f32 v49, v20, v21
	v_cvt_pk_fp8_f32 v50, v24, v25
	v_cvt_pk_fp8_f32 v51, v28, v29
	v_cvt_pk_fp8_f32 v48, v18, v19 op_sel:[0,0,1]
	v_cvt_pk_fp8_f32 v49, v22, v23 op_sel:[0,0,1]
	v_cvt_pk_fp8_f32 v50, v26, v27 op_sel:[0,0,1]
	v_cvt_pk_fp8_f32 v51, v30, v31 op_sel:[0,0,1]
	v_div_scale_f32 v11, s[50:51], v8, v8, v10
	v_rcp_f32_e32 v12, v11
	v_div_scale_f32 v13, vcc, v10, v8, v10
	v_fma_f32 v14, -v11, v12, 1.0
	v_fmac_f32_e32 v12, v14, v12
	v_mul_f32_e32 v14, v13, v12
	v_fma_f32 v15, -v11, v14, v13
	v_fmac_f32_e32 v14, v15, v12
	v_fma_f32 v11, -v11, v14, v13
	v_div_fmas_f32 v11, v11, v12, v14
	v_div_fixup_f32 v11, v11, v8, v10
	v_cndmask_b32_e64 v11, 1.0, v11, s[70:71]
	global_store_dwordx4 v1, v[48:51], s[46:47]
	s_mov_b64 exec, 1
	global_store_dword v9, v11, s[48:49]
	s_mov_b64 exec, -1
.Lcv_done:
	ds_read_b32 v0, v245 offset:0
	ds_read_b32 v1, v245 offset:1024
	ds_read_b32 v2, v245 offset:2048
	ds_read_b32 v3, v245 offset:3072
	ds_read_b32 v4, v245 offset:4096
	ds_read_b32 v5, v245 offset:5120
	ds_read_b32 v6, v245 offset:6144
	ds_read_b32 v7, v245 offset:7168
	ds_read_b32 v8, v245 offset:8192
	ds_read_b32 v9, v245 offset:9216
	ds_read_b32 v10, v245 offset:10240
	ds_read_b32 v11, v245 offset:11264
	ds_read_b32 v12, v245 offset:12288
	ds_read_b32 v13, v245 offset:13312
	ds_read_b32 v14, v245 offset:14336
	ds_read_b32 v15, v245 offset:15360
	ds_read_b32 v16, v245 offset:16384
	ds_read_b32 v17, v245 offset:17408
	ds_read_b32 v18, v245 offset:18432
	ds_read_b32 v19, v245 offset:19456
	ds_read_b32 v20, v245 offset:20480
	ds_read_b32 v21, v245 offset:21504
	ds_read_b32 v22, v245 offset:22528
	ds_read_b32 v23, v245 offset:23552
	ds_read_b32 v24, v245 offset:24576
	ds_read_b32 v25, v245 offset:25600
	ds_read_b32 v26, v245 offset:26624
	ds_read_b32 v27, v245 offset:27648
	ds_read_b32 v28, v245 offset:28672
	ds_read_b32 v29, v245 offset:29696
	ds_read_b32 v30, v245 offset:30720
	ds_read_b32 v31, v245 offset:31744
	ds_read_b32 v32, v245 offset:32768
	ds_read_b32 v33, v245 offset:33792
	ds_read_b32 v34, v245 offset:34816
	ds_read_b32 v35, v245 offset:35840
	ds_read_b32 v36, v245 offset:36864
	ds_read_b32 v37, v245 offset:37888
	ds_read_b32 v38, v245 offset:38912
	ds_read_b32 v39, v245 offset:39936
	ds_read_b32 v40, v245 offset:40960
	ds_read_b32 v41, v245 offset:41984
	ds_read_b32 v42, v245 offset:43008
	ds_read_b32 v43, v245 offset:44032
	ds_read_b32 v44, v245 offset:45056
	ds_read_b32 v45, v245 offset:46080
	ds_read_b32 v46, v245 offset:47104
	ds_read_b32 v47, v245 offset:48128
	ds_read_b32 v48, v245 offset:49152
	ds_read_b32 v49, v245 offset:50176
	ds_read_b32 v50, v245 offset:51200
	ds_read_b32 v51, v245 offset:52224
	s_waitcnt lgkmcnt(0)
	s_mov_b64 exec, s[66:67]
	v_readlane_b32 s10, v244, 0
	v_readlane_b32 s11, v244, 1
	v_readlane_b32 s12, v244, 2
	v_readlane_b32 s13, v244, 3
	v_readlane_b32 s40, v244, 4
	v_readlane_b32 s41, v244, 5
	v_readlane_b32 s42, v244, 6
	v_readlane_b32 s43, v244, 7
	v_readlane_b32 s44, v244, 8
	v_readlane_b32 s45, v244, 9
	v_readlane_b32 s46, v244, 10
	v_readlane_b32 s47, v244, 11
	v_readlane_b32 s48, v244, 12
	v_readlane_b32 s49, v244, 13
	v_readlane_b32 s50, v244, 14
	v_readlane_b32 s51, v244, 15
	v_readlane_b32 s58, v244, 16
	v_readlane_b32 s59, v244, 17
	v_readlane_b32 s60, v244, 18
	v_readlane_b32 s61, v244, 19
	v_readlane_b32 s62, v244, 20
	v_readlane_b32 s63, v244, 21
	v_readlane_b32 s64, v244, 22
	v_readlane_b32 s65, v244, 23
	v_readlane_b32 s66, v244, 24
	v_readlane_b32 s67, v244, 25
	v_readlane_b32 s68, v244, 26
	v_readlane_b32 s70, v244, 27
	v_readlane_b32 s71, v244, 28
	v_readlane_b32 vcc_lo, v244, 29
	v_readlane_b32 vcc_hi, v244, 30
	v_readlane_b32 s0, v248, 0
	v_readlane_b32 s1, v248, 1
	s_load_dwordx4 s[24:27], s[0:1], 0xe0
	s_waitcnt lgkmcnt(0)
	s_cmp_gt_i32 s25, 7
	s_cbranch_scc0 .LBB0_862
	s_waitcnt vmcnt(0)
	s_barrier
	s_mov_b64 s[0:1], exec
	v_readlane_b32 s2, v248, 9
	v_readlane_b32 s3, v248, 10
	s_and_b64 s[2:3], s[0:1], s[2:3]
	s_mov_b64 exec, s[2:3]
	s_cbranch_execz .LBB0_861
	s_mov_b64 s[2:3], src_shared_base
	v_mov_b32_e32 v0, 0x12300
	v_mov_b32_e32 v1, s3
	s_waitcnt vmcnt(0) expcnt(0) lgkmcnt(0)
	flat_load_dword v2, v[0:1] sc0 sc1
	s_waitcnt vmcnt(0)
	v_mov_b32_e32 v0, 0x12304
	flat_load_dword v0, v[0:1] sc0 sc1
	s_waitcnt vmcnt(0) lgkmcnt(0)
	v_cmp_eq_u32_e32 vcc, 0, v2
	s_and_saveexec_b64 s[2:3], vcc
	s_cbranch_execz .LBB0_839
	v_readlane_b32 s10, v248, 56
	v_readlane_b32 s11, v248, 57
	s_load_dword s10, s[10:11], 0x0
	v_mov_b32_e32 v1, 0
	v_mov_b32_e32 v2, 0
	s_branch .LBB0_836

; __device__ void phase_ffn_norm(const Params& p) {
;     ...
;   unsigned char* q8 = (unsigned char*)(ws + W_F); float* qs = (float*)(ws + W_F + 33554432);
;   for (int r = gw; r < 2 * 16384; r += nw) {
;     const float* src = (r < 16384) ? p.in[22] + (size_t)r * DM : p.in[23] + (size_t)(r - 16384) * DM;
.LBB0_946:
	s_or_b64 exec, exec, s[0:1]
	s_mov_b64 s[0:1], exec
	v_readlane_b32 s2, v247, 42
	v_readlane_b32 s3, v247, 43
	s_and_b64 s[2:3], s[0:1], s[2:3]
	s_mov_b64 exec, s[2:3]
	s_branch .LBB0_951
	v_cmp_lt_i32_e32 vcc, v41, v40
	s_mov_b64 s[2:3], 0
	v_mov_b64_e32 v[2:3], v[26:27]
	v_cndmask_b32_e32 v0, v39, v41, vcc
	v_cmp_lt_i32_e32 vcc, v42, v40
	v_lshlrev_b32_e32 v6, 2, v0
	v_mov_b64_e32 v[4:5], v[18:19]
	v_cndmask_b32_e32 v0, v39, v42, vcc
	v_cmp_lt_i32_e32 vcc, v43, v40
	v_lshlrev_b32_e32 v7, 2, v0
	s_nop 0
	v_cndmask_b32_e32 v0, v39, v43, vcc
	v_cmp_lt_i32_e32 vcc, v44, v40
	v_lshlrev_b32_e32 v8, 2, v0
	s_nop 0
	v_cndmask_b32_e32 v0, v39, v44, vcc
	v_cmp_lt_i32_e32 vcc, v45, v40
	v_lshlrev_b32_e32 v9, 2, v0
	s_nop 0
	v_cndmask_b32_e32 v0, v39, v45, vcc
	v_cmp_lt_i32_e32 vcc, v46, v40
	v_lshlrev_b32_e32 v10, 2, v0
	s_nop 0
	v_cndmask_b32_e32 v0, v39, v46, vcc
	v_lshlrev_b32_e32 v11, 2, v0
	v_mov_b64_e32 v[0:1], v[12:13]
	s_branch .LBB0_949

.LBB0_1161:
	s_cmp_gt_i32 s40, 11
	s_cselect_b64 s[0:1], -1, 0
	s_cmp_lt_i32 s41, 12
	s_cselect_b64 s[2:3], -1, 0
	s_or_b64 s[0:1], s[0:1], s[2:3]
	s_and_b64 vcc, exec, s[0:1]
	s_cbranch_vccnz .LBB0_1248
; __device__ __forceinline__ float bflo(unsigned w) { return __uint_as_float(w << 16); }
; __device__ __forceinline__ float bfhi(unsigned w) { return __uint_as_float(w & 0xffff0000u); }
; __device__ __forceinline__ void peer_token_part(const Params& p, int t, int e_lo, int e_hi, float (&ov)[16], int lane) {
;   char* ws = p.ws;
;   const bf16_t* hf = (const bf16_t*)(ws + W_C);
;   const unsigned char* u8 = (const unsigned char*)(ws + W_F); const unsigned char* v8 = u8 + 1024;
;   const float* qs = (const float*)(ws + W_F + 33554432);
;   const int* seli = (const int*)(ws + D_SELI); const float* selw = (const float*)(ws + D_SELW);
;   f32v2_t hv[8], o2[8];
;   {
;     u32x4 a = *(const u32x4*)(hf + (size_t)t * LDH + lane * 16), b = *(const u32x4*)(hf + (size_t)t * LDH + lane * 16 + 8);
; #pragma unroll
;     for (int i = 0; i < 4; ++i) { hv[i] = (f32v2_t){bflo(a[i]), bfhi(a[i])}; hv[4 + i] = (f32v2_t){bflo(b[i]), bfhi(b[i])}; }
; #pragma unroll
;     for (int i = 0; i < 8; ++i) o2[i] = (f32v2_t){ov[2 * i], ov[2 * i + 1]};
;   }
;   const int myi0 = seli[(size_t)t * 128 + lane], myi1 = seli[(size_t)t * 128 + 64 + lane];
;   const float mysu0 = qs[myi0], mysu1 = qs[myi1];
;   const float myw0 = selw[(size_t)t * 128 + lane] * qs[16384 + myi0], myw1 = selw[(size_t)t * 128 + 64 + lane] * qs[16384 + myi1];
;   const int b0 = lane & 1, b1 = lane & 2, b2 = lane & 4;
; __device__ void phase_peer_gather(const Params& p, char* lds) {
;   const int wid = threadIdx.x >> 6, lane = threadIdx.x & 63;
;   const int gw = blockIdx.x * 4 + wid, nw = gridDim.x * 4;
;   const int t_main = (T / nw) * nw;
;   for (int t = gw; t < t_main; t += nw) {
	v_readlane_b32 s0, v248, 0
	v_readlane_b32 s1, v248, 1
	s_load_dword s26, s[0:1], 0xf0
	s_bfe_u32 s95, s42, 0x1000b
	s_add_u32 s0, s0, 0xf0
	s_addc_u32 s1, s1, 0
	v_writelane_b32 v247, s0, 8
	s_waitcnt lgkmcnt(0)
	s_lshl_b32 s27, s26, 2
	v_mov_b32_e32 v81, 0
	v_writelane_b32 v247, s1, 9
	s_abs_i32 s0, s27
	v_cvt_f32_u32_e32 v0, s0
	s_sub_i32 s1, 0, s0
	v_mov_b32_e32 v1, v81
	v_lshlrev_b32_e32 v80, 4, v180
	v_rcp_iflag_f32_e32 v0, v0
	s_waitcnt vmcnt(0)
	v_lshl_add_u32 v120, s72, 2, v185
	v_mbcnt_hi_u32_b32 v128, -1, v221
	v_and_b32_e32 v2, 4, v181
	v_mul_f32_e32 v0, 0x4f7ffffe, v0
	v_cvt_u32_f32_e32 v0, v0
	v_and_b32_e32 v3, 2, v181
	v_and_b32_e32 v4, 1, v181
	v_and_b32_e32 v5, 7, v181
	v_readfirstlane_b32 s2, v0
	s_mul_i32 s1, s1, s2
	s_mul_hi_u32 s1, s2, s1
	s_add_i32 s2, s2, s1
	s_mul_hi_u32 s1, s2, 0x8200
	s_mul_i32 s1, s1, s0
	s_sub_i32 s1, 0x8200, s1
	s_sub_i32 s2, s1, s0
	s_cmp_ge_u32 s1, s0
	s_cselect_b32 s1, s2, s1
	s_sub_i32 s2, s1, s0
	s_cmp_ge_u32 s1, s0
	s_cselect_b32 s0, s2, s1
	s_sub_i32 s29, 0x8200, s0
	s_add_i32 s0, s29, s72
	s_cmp_lt_i32 s0, 0x8200
	v_writelane_b32 v248, s0, 27
	s_cselect_b64 s[0:1], -1, 0
	v_writelane_b32 v247, s0, 50
	v_lshlrev_b32_e32 v0, 5, v180
	s_add_u32 s36, s96, 0x1228e000
	v_writelane_b32 v247, s1, 51
	v_lshl_add_u64 v[0:1], s[96:97], 0, v[0:1]
	s_mov_b64 s[0:1], 0x5b7e000
	s_addc_u32 s37, s97, 0
	v_lshl_add_u64 v[82:83], v[0:1], 0, s[0:1]
	v_lshl_add_u64 v[0:1], s[96:97], 0, v[80:81]
	s_mov_b64 s[0:1], 0x1489e000
	s_add_u32 s16, s96, 0x1689e000
	v_lshl_add_u64 v[84:85], v[0:1], 0, s[0:1]
	s_mov_b64 s[0:1], 0x1489e400
	v_lshlrev_b32_e32 v80, 6, v180
	s_addc_u32 s17, s97, 0
	v_lshl_add_u64 v[86:87], v[0:1], 0, s[0:1]
	v_lshl_add_u64 v[0:1], s[96:97], 0, v[80:81]
	s_mov_b64 s[0:1], 0xa08e000
	s_add_u32 s18, s96, 0x132ce000
	v_lshl_add_u64 v[88:89], v[0:1], 0, s[0:1]
	v_readlane_b32 s0, v248, 2
	s_addc_u32 s19, s97, 0
	v_readlane_b32 s1, v248, 3
	v_readlane_b32 s2, v248, 4
	v_readlane_b32 s3, v248, 5
	v_lshl_add_u64 v[90:91], s[0:1], 0, v[80:81]
	global_load_dwordx4 v[154:157], v[90:91], off
	global_load_dwordx4 v[158:161], v[90:91], off offset:16
	global_load_dwordx4 v[162:165], v[90:91], off offset:32
	global_load_dwordx4 v[166:169], v[90:91], off offset:48
	s_add_u32 s0, s96, 0x166a400
	s_addc_u32 s1, s97, 0
	v_writelane_b32 v248, s0, 35
	v_lshl_add_u64 v[92:93], s[2:3], 0, v[80:81]
	v_lshlrev_b32_e32 v0, 1, v181
	v_writelane_b32 v248, s1, 36
	v_lshlrev_b32_e32 v121, 5, v185
	v_readlane_b32 s2, v248, 8
	s_cmp_eq_u32 s2, 0
	s_cselect_b64 s[0:1], -1, 0
	v_writelane_b32 v248, s0, 33
	v_and_b32_e32 v129, 64, v128
	s_mov_b32 s28, 0
	v_writelane_b32 v248, s1, 34
	s_add_u32 s0, s96, 0x166a500
	s_addc_u32 s1, s97, 0
	v_writelane_b32 v248, s0, 11
	s_cmp_eq_u32 s2, 1
	v_add_u32_e32 v122, 32, v121
	v_writelane_b32 v248, s1, 12
	s_cselect_b64 s[0:1], -1, 0
	v_writelane_b32 v248, s0, 54
	v_lshl_or_b32 v123, v185, 12, v80
	v_lshlrev_b32_e32 v125, 2, v5
	v_writelane_b32 v248, s1, 55
	s_add_u32 s0, s96, 0x166a600
	s_addc_u32 s1, s97, 0
	v_writelane_b32 v248, s0, 0
	s_cmp_eq_u32 s2, 2
	s_mov_b32 s33, 0x10000
	v_writelane_b32 v248, s1, 1
	s_cselect_b64 s[0:1], -1, 0
	s_add_u32 s88, s96, 0x166a700
	s_addc_u32 s89, s97, 0
	v_writelane_b32 v248, s0, 58
	s_cmp_eq_u32 s2, 3
	v_mov_b32_e32 v126, 0x3ba10414
	v_writelane_b32 v248, s1, 59
	s_cselect_b64 s[0:1], -1, 0
	s_add_u32 s86, s96, 0x166a800
	s_addc_u32 s87, s97, 0
	v_writelane_b32 v248, s0, 62
	s_cmp_eq_u32 s2, 4
	v_mov_b32_e32 v127, 0x358637bd
	v_writelane_b32 v248, s1, 63
	s_cselect_b64 s[0:1], -1, 0
	s_add_u32 s84, s96, 0x166a900
	s_addc_u32 s85, s97, 0
	v_writelane_b32 v247, s0, 2
	s_cmp_eq_u32 s2, 5
	v_xor_b32_e32 v130, 1, v128
	v_writelane_b32 v247, s1, 3
	s_cselect_b64 s[0:1], -1, 0
	v_writelane_b32 v247, s0, 6
	v_add_u32_e32 v131, 64, v129
	v_xor_b32_e32 v132, 2, v128
	v_writelane_b32 v247, s1, 7
	s_add_u32 s0, s96, 0x166aa00
	s_addc_u32 s1, s97, 0
	s_cmp_eq_u32 s2, 6
	s_cselect_b64 s[4:5], -1, 0
	v_writelane_b32 v247, s4, 10
	v_xor_b32_e32 v133, 4, v128
	v_xor_b32_e32 v134, 8, v128
	v_writelane_b32 v247, s5, 11
	s_add_u32 s4, s96, 0x166ab00
	s_addc_u32 s5, s97, 0
	s_cmp_eq_u32 s2, 7
	s_cselect_b64 s[6:7], -1, 0
	v_writelane_b32 v247, s6, 14
	v_xor_b32_e32 v135, 16, v128
	v_xor_b32_e32 v136, 32, v128
	v_writelane_b32 v247, s7, 15
	s_add_u32 s6, s96, 0x166ac00
	s_addc_u32 s7, s97, 0
	s_cmp_eq_u32 s2, 8
	s_cselect_b64 s[8:9], -1, 0
	v_writelane_b32 v247, s8, 18
	v_or_b32_e32 v137, v129, v5
	v_mov_b32_e32 v138, 0xb9c68948
	v_writelane_b32 v247, s9, 19
	s_add_u32 s8, s96, 0x166ad00
	s_addc_u32 s9, s97, 0
	s_cmp_eq_u32 s2, 9
	s_cselect_b64 s[10:11], -1, 0
	v_writelane_b32 v247, s10, 22
	v_mov_b32_e32 v139, 0x7f800000
	v_mov_b32_e32 v140, 0x880
	v_writelane_b32 v247, s11, 23
	s_add_u32 s10, s96, 0x166ae00
	s_addc_u32 s11, s97, 0
	s_cmp_eq_u32 s2, 10
	s_cselect_b64 s[12:13], -1, 0
	v_writelane_b32 v247, s12, 26
	v_mov_b32_e32 v94, 0x12300
	v_mov_b32_e32 v96, 0x12304
	v_writelane_b32 v247, s13, 27
	s_add_u32 s12, s96, 0x166af00
	s_addc_u32 s13, s97, 0
	s_cmp_eq_u32 s2, 11
	s_cselect_b64 s[14:15], -1, 0
	v_writelane_b32 v247, s14, 30
	s_mov_b32 s34, 0xbcc618b2
	s_mov_b32 s35, 0x3dda74e4
	v_writelane_b32 v247, s15, 31
	s_add_u32 s14, s96, 0x166b000
	s_addc_u32 s15, s97, 0
	s_cmp_eq_u32 s2, 12
	s_cselect_b64 s[20:21], -1, 0
	v_writelane_b32 v247, s20, 34
	s_mov_b32 s82, 0x3f228afd
	s_mov_b32 s83, 0x3e03c728
	v_writelane_b32 v247, s21, 35
	s_add_u32 s20, s96, 0x166b100
	s_addc_u32 s21, s97, 0
	s_cmp_eq_u32 s2, 13
	s_cselect_b64 s[22:23], -1, 0
	v_writelane_b32 v247, s22, 38
	s_mov_b32 s90, 0xbfb8aa3b
	s_mov_b32 s91, 0x42ce8ed0
	v_writelane_b32 v247, s23, 39
	s_add_u32 s22, s96, 0x166b200
	s_addc_u32 s23, s97, 0
	s_cmp_eq_u32 s2, 14
	s_cselect_b64 s[24:25], -1, 0
	v_writelane_b32 v247, s24, 42
	s_mov_b32 s92, 0xc2b17218
	s_brev_b32 s93, -2
	v_writelane_b32 v247, s25, 43
	s_add_u32 s24, s96, 0x166b300
	s_addc_u32 s25, s97, 0
	s_cmp_eq_u32 s2, 15
	s_cselect_b64 s[30:31], -1, 0
	v_writelane_b32 v247, s30, 46
	s_lshl_b32 s2, s2, 8
	s_mov_b32 s94, 0x800000
	v_writelane_b32 v247, s31, 47
	v_readlane_b32 s30, v248, 6
	v_readlane_b32 s31, v248, 7
	s_add_u32 s2, s30, s2
	s_addc_u32 s3, s31, 0
	s_add_u32 s30, s2, 0x1400
	s_addc_u32 s31, s3, 0
	v_writelane_b32 v248, s30, 60
	s_add_u32 s2, s2, 0x2400
	s_addc_u32 s3, s3, 0
	v_writelane_b32 v248, s31, 61
	v_writelane_b32 v248, s2, 56
	s_mov_b32 s30, 0x378e98ab
	s_mov_b32 s31, 0x3b7cd369
	v_writelane_b32 v248, s3, 57
	s_add_u32 s2, s96, 0x166d400
	s_addc_u32 s3, s97, 0
	v_writelane_b32 v247, s2, 4
	v_cmp_eq_u32_e64 s[38:39], 0, v4
	v_cmp_eq_u32_e64 s[40:41], 0, v3
	v_writelane_b32 v247, s3, 5
	s_add_u32 s2, s96, 0x166d500
	s_addc_u32 s3, s97, 0
	v_writelane_b32 v247, s2, 0
	v_cmp_eq_u32_e64 s[42:43], 0, v2
	v_cmp_gt_u32_e64 s[44:45], 64, v181
	v_writelane_b32 v247, s3, 1
	s_movk_i32 s2, 0x80
	v_and_or_b32 v124, v0, s2, 28
	v_cmp_gt_i32_e64 s[2:3], s29, v120
	v_cmp_lt_u32_e64 s[46:47], 63, v181
	s_nop 0
	v_writelane_b32 v246, s2, 14
	s_nop 1
	v_writelane_b32 v246, s3, 15
	s_branch .LBB0_1166
